# P8 epilogue y stores made nontemporal (output never read back)
# speedup vs baseline: 1.0054x; 1.0038x over previous
.LBB0_941:
	s_lshl_b32 s2, s86, 8
	s_add_i32 s3, s2, 0xffffe000
	s_ashr_i32 s3, s3, 10
	s_add_i32 s3, s3, 1
	s_cmp_gt_i32 s86, 31
	s_cselect_b32 s21, s3, 0
	s_ashr_i32 s3, s2, 31
	s_lshl_b64 s[26:27], s[2:3], 14
	s_mul_hi_i32 s3, s21, 0x18000
	s_mul_i32 s21, s21, 0x18000
	s_add_u32 s34, s76, s21
	s_addc_u32 s35, s77, s3
	s_mul_i32 s3, s86, 0x208000
	v_lshl_or_b32 v128, s30, 8, v183
	s_mul_hi_i32 s21, s2, 0x2080
	s_add_u32 s2, s96, s3
	v_ashrrev_i32_e32 v129, 31, v128
	s_addc_u32 s3, s97, s21
	v_lshl_add_u64 v[180:181], v[128:129], 1, s[2:3]
	v_lshl_add_u64 v[196:197], v[180:181], 0, v[160:161]
	global_load_dwordx4 v[188:191], v[196:197], off nt
	v_lshlrev_b64 v[178:179], 2, v[128:129]
	v_lshl_add_u64 v[192:193], s[34:35], 0, v[178:179]
	global_load_dwordx4 v[132:135], v[192:193], off
	global_load_dwordx4 v[128:131], v[192:193], off offset:16
	ds_bpermute_b32 v194, v184, v124
	ds_bpermute_b32 v195, v184, v125
	ds_bpermute_b32 v198, v184, v126
	ds_bpermute_b32 v199, v184, v127
	ds_bpermute_b32 v200, v184, v120
	ds_bpermute_b32 v201, v184, v121
	ds_bpermute_b32 v202, v184, v122
	ds_bpermute_b32 v203, v184, v123
	s_add_u32 s2, s48, s26
	s_addc_u32 s3, s49, s27
	global_load_dwordx4 v[120:123], v[192:193], off offset:528
	global_load_dwordx4 v[124:127], v[192:193], off offset:512
	v_lshl_add_u64 v[178:179], s[2:3], 0, v[178:179]
	v_lshl_add_u64 v[204:205], v[178:179], 0, v[144:145]
	ds_bpermute_b32 v116, v184, v116
	ds_bpermute_b32 v117, v184, v117
	ds_bpermute_b32 v118, v184, v118
	ds_bpermute_b32 v119, v184, v119
	ds_bpermute_b32 v108, v184, v108
	ds_bpermute_b32 v109, v184, v109
	ds_bpermute_b32 v110, v184, v110
	ds_bpermute_b32 v111, v184, v111
	ds_bpermute_b32 v100, v184, v100
	ds_bpermute_b32 v101, v184, v101
	ds_bpermute_b32 v102, v184, v102
	ds_bpermute_b32 v103, v184, v103
	ds_bpermute_b32 v92, v184, v92
	ds_bpermute_b32 v93, v184, v93
	ds_bpermute_b32 v94, v184, v94
	ds_bpermute_b32 v95, v184, v95
	ds_bpermute_b32 v84, v184, v84
	ds_bpermute_b32 v85, v184, v85
	ds_bpermute_b32 v86, v184, v86
	ds_bpermute_b32 v87, v184, v87
	ds_bpermute_b32 v76, v184, v76
	ds_bpermute_b32 v77, v184, v77
	ds_bpermute_b32 v78, v184, v78
	ds_bpermute_b32 v79, v184, v79
	ds_bpermute_b32 v68, v184, v68
	ds_bpermute_b32 v69, v184, v69
	ds_bpermute_b32 v70, v184, v70
	ds_bpermute_b32 v71, v184, v71
	ds_bpermute_b32 v60, v184, v60
	ds_bpermute_b32 v61, v184, v61
	ds_bpermute_b32 v62, v184, v62
	ds_bpermute_b32 v63, v184, v63
	ds_bpermute_b32 v52, v184, v52
	ds_bpermute_b32 v53, v184, v53
	ds_bpermute_b32 v54, v184, v54
	ds_bpermute_b32 v55, v184, v55
	ds_bpermute_b32 v44, v184, v44
	ds_bpermute_b32 v45, v184, v45
	ds_bpermute_b32 v46, v184, v46
	ds_bpermute_b32 v47, v184, v47
	ds_bpermute_b32 v36, v184, v36
	ds_bpermute_b32 v37, v184, v37
	ds_bpermute_b32 v38, v184, v38
	ds_bpermute_b32 v39, v184, v39
	ds_bpermute_b32 v28, v184, v28
	ds_bpermute_b32 v29, v184, v29
	ds_bpermute_b32 v30, v184, v30
	ds_bpermute_b32 v31, v184, v31
	ds_bpermute_b32 v20, v184, v20
	ds_bpermute_b32 v21, v184, v21
	ds_bpermute_b32 v22, v184, v22
	ds_bpermute_b32 v23, v184, v23
	ds_bpermute_b32 v12, v184, v12
	ds_bpermute_b32 v13, v184, v13
	ds_bpermute_b32 v14, v184, v14
	ds_bpermute_b32 v15, v184, v15
	ds_bpermute_b32 v4, v184, v4
	ds_bpermute_b32 v5, v184, v5
	ds_bpermute_b32 v6, v184, v6
	ds_bpermute_b32 v7, v184, v7
	s_andn2_b64 vcc, exec, s[28:29]
	s_mov_b64 s[2:3], -1
	s_waitcnt vmcnt(0)
	v_lshlrev_b32_e32 v192, 16, v188
	v_and_b32_e32 v193, 0xffff0000, v188
	v_lshlrev_b32_e32 v206, 16, v189
	v_and_b32_e32 v207, 0xffff0000, v189
	v_lshlrev_b32_e32 v208, 16, v190
	v_and_b32_e32 v209, 0xffff0000, v190
	v_lshlrev_b32_e32 v210, 16, v191
	v_and_b32_e32 v211, 0xffff0000, v191
	s_waitcnt lgkmcnt(14)
	v_pk_fma_f32 v[188:189], v[132:133], v[194:195], v[192:193]
	v_pk_fma_f32 v[190:191], v[134:135], v[198:199], v[206:207]
	v_pk_fma_f32 v[192:193], v[128:129], v[200:201], v[208:209]
	v_pk_fma_f32 v[194:195], v[130:131], v[202:203], v[210:211]
	global_store_dwordx4 v[204:205], v[188:191], off nt
	global_store_dwordx4 v[204:205], v[192:195], off offset:16 nt
	global_load_dwordx4 v[188:191], v[196:197], off offset:256 nt
	ds_bpermute_b32 v192, v184, v112
	ds_bpermute_b32 v193, v184, v113
	ds_bpermute_b32 v194, v184, v114
	ds_bpermute_b32 v195, v184, v115
	v_lshl_add_u64 v[196:197], v[180:181], 0, v[162:163]
	s_waitcnt vmcnt(0)
	v_lshlrev_b32_e32 v112, 16, v188
	v_and_b32_e32 v113, 0xffff0000, v188
	v_lshlrev_b32_e32 v114, 16, v189
	v_and_b32_e32 v115, 0xffff0000, v189
	v_lshlrev_b32_e32 v188, 16, v190
	v_and_b32_e32 v189, 0xffff0000, v190
	v_lshlrev_b32_e32 v190, 16, v191
	v_and_b32_e32 v191, 0xffff0000, v191
	v_pk_fma_f32 v[114:115], v[126:127], v[118:119], v[114:115]
	v_pk_fma_f32 v[112:113], v[124:125], v[116:117], v[112:113]
	s_waitcnt lgkmcnt(0)
	v_pk_fma_f32 v[118:119], v[122:123], v[194:195], v[190:191]
	v_pk_fma_f32 v[116:117], v[120:121], v[192:193], v[188:189]
	global_store_dwordx4 v[204:205], v[112:115], off offset:512 nt
	global_store_dwordx4 v[204:205], v[116:119], off offset:528 nt
	global_load_dwordx4 v[112:115], v[196:197], off nt
	ds_bpermute_b32 v116, v184, v104
	ds_bpermute_b32 v117, v184, v105
	ds_bpermute_b32 v118, v184, v106
	ds_bpermute_b32 v119, v184, v107
	v_lshl_add_u64 v[188:189], v[178:179], 0, v[146:147]
	s_waitcnt vmcnt(0)
	v_lshlrev_b32_e32 v104, 16, v112
	v_and_b32_e32 v105, 0xffff0000, v112
	v_lshlrev_b32_e32 v106, 16, v113
	v_and_b32_e32 v107, 0xffff0000, v113
	v_lshlrev_b32_e32 v112, 16, v114
	v_and_b32_e32 v113, 0xffff0000, v114
	v_lshlrev_b32_e32 v114, 16, v115
	v_and_b32_e32 v115, 0xffff0000, v115
	v_pk_fma_f32 v[106:107], v[134:135], v[110:111], v[106:107]
	v_pk_fma_f32 v[104:105], v[132:133], v[108:109], v[104:105]
	s_waitcnt lgkmcnt(0)
	v_pk_fma_f32 v[110:111], v[130:131], v[118:119], v[114:115]
	v_pk_fma_f32 v[108:109], v[128:129], v[116:117], v[112:113]
	global_store_dwordx4 v[188:189], v[104:107], off nt
	global_store_dwordx4 v[188:189], v[108:111], off offset:16 nt
	global_load_dwordx4 v[104:107], v[196:197], off offset:256 nt
	ds_bpermute_b32 v108, v184, v96
	ds_bpermute_b32 v109, v184, v97
	ds_bpermute_b32 v110, v184, v98
	ds_bpermute_b32 v111, v184, v99
	v_lshl_add_u64 v[112:113], v[180:181], 0, v[164:165]
	s_waitcnt vmcnt(0)
	v_lshlrev_b32_e32 v96, 16, v104
	v_and_b32_e32 v97, 0xffff0000, v104
	v_lshlrev_b32_e32 v98, 16, v105
	v_and_b32_e32 v99, 0xffff0000, v105
	v_lshlrev_b32_e32 v104, 16, v106
	v_and_b32_e32 v105, 0xffff0000, v106
	v_lshlrev_b32_e32 v106, 16, v107
	v_and_b32_e32 v107, 0xffff0000, v107
	v_pk_fma_f32 v[98:99], v[126:127], v[102:103], v[98:99]
	v_pk_fma_f32 v[96:97], v[124:125], v[100:101], v[96:97]
	s_waitcnt lgkmcnt(0)
	v_pk_fma_f32 v[102:103], v[122:123], v[110:111], v[106:107]
	v_pk_fma_f32 v[100:101], v[120:121], v[108:109], v[104:105]
	global_store_dwordx4 v[188:189], v[96:99], off offset:512 nt
	global_store_dwordx4 v[188:189], v[100:103], off offset:528 nt
	global_load_dwordx4 v[96:99], v[112:113], off nt
	ds_bpermute_b32 v100, v184, v88
	ds_bpermute_b32 v101, v184, v89
	ds_bpermute_b32 v102, v184, v90
	ds_bpermute_b32 v103, v184, v91
	v_lshl_add_u64 v[104:105], v[178:179], 0, v[148:149]
	s_waitcnt vmcnt(0)
	v_lshlrev_b32_e32 v88, 16, v96
	v_and_b32_e32 v89, 0xffff0000, v96
	v_lshlrev_b32_e32 v90, 16, v97
	v_and_b32_e32 v91, 0xffff0000, v97
	v_lshlrev_b32_e32 v96, 16, v98
	v_and_b32_e32 v97, 0xffff0000, v98
	v_lshlrev_b32_e32 v98, 16, v99
	v_and_b32_e32 v99, 0xffff0000, v99
	v_pk_fma_f32 v[90:91], v[134:135], v[94:95], v[90:91]
	v_pk_fma_f32 v[88:89], v[132:133], v[92:93], v[88:89]
	s_waitcnt lgkmcnt(0)
	v_pk_fma_f32 v[94:95], v[130:131], v[102:103], v[98:99]
	v_pk_fma_f32 v[92:93], v[128:129], v[100:101], v[96:97]
	global_store_dwordx4 v[104:105], v[88:91], off nt
	global_store_dwordx4 v[104:105], v[92:95], off offset:16 nt
	global_load_dwordx4 v[88:91], v[112:113], off offset:256 nt
	ds_bpermute_b32 v92, v184, v80
	ds_bpermute_b32 v93, v184, v81
	ds_bpermute_b32 v94, v184, v82
	ds_bpermute_b32 v95, v184, v83
	v_lshl_add_u64 v[96:97], v[180:181], 0, v[166:167]
	s_waitcnt vmcnt(0)
	v_lshlrev_b32_e32 v80, 16, v88
	v_and_b32_e32 v81, 0xffff0000, v88
	v_lshlrev_b32_e32 v82, 16, v89
	v_and_b32_e32 v83, 0xffff0000, v89
	v_lshlrev_b32_e32 v88, 16, v90
	v_and_b32_e32 v89, 0xffff0000, v90
	v_lshlrev_b32_e32 v90, 16, v91
	v_and_b32_e32 v91, 0xffff0000, v91
	v_pk_fma_f32 v[82:83], v[126:127], v[86:87], v[82:83]
	v_pk_fma_f32 v[80:81], v[124:125], v[84:85], v[80:81]
	s_waitcnt lgkmcnt(0)
	v_pk_fma_f32 v[86:87], v[122:123], v[94:95], v[90:91]
	v_pk_fma_f32 v[84:85], v[120:121], v[92:93], v[88:89]
	global_store_dwordx4 v[104:105], v[80:83], off offset:512 nt
	global_store_dwordx4 v[104:105], v[84:87], off offset:528 nt
	global_load_dwordx4 v[80:83], v[96:97], off nt
	ds_bpermute_b32 v84, v184, v72
	ds_bpermute_b32 v85, v184, v73
	ds_bpermute_b32 v86, v184, v74
	ds_bpermute_b32 v87, v184, v75
	v_lshl_add_u64 v[88:89], v[178:179], 0, v[150:151]
	s_waitcnt vmcnt(0)
	v_lshlrev_b32_e32 v72, 16, v80
	v_and_b32_e32 v73, 0xffff0000, v80
	v_lshlrev_b32_e32 v74, 16, v81
	v_and_b32_e32 v75, 0xffff0000, v81
	v_lshlrev_b32_e32 v80, 16, v82
	v_and_b32_e32 v81, 0xffff0000, v82
	v_lshlrev_b32_e32 v82, 16, v83
	v_and_b32_e32 v83, 0xffff0000, v83
	v_pk_fma_f32 v[74:75], v[134:135], v[78:79], v[74:75]
	v_pk_fma_f32 v[72:73], v[132:133], v[76:77], v[72:73]
	s_waitcnt lgkmcnt(0)
	v_pk_fma_f32 v[78:79], v[130:131], v[86:87], v[82:83]
	v_pk_fma_f32 v[76:77], v[128:129], v[84:85], v[80:81]
	global_store_dwordx4 v[88:89], v[72:75], off nt
	global_store_dwordx4 v[88:89], v[76:79], off offset:16 nt
	global_load_dwordx4 v[72:75], v[96:97], off offset:256 nt
	ds_bpermute_b32 v76, v184, v64
	ds_bpermute_b32 v77, v184, v65
	ds_bpermute_b32 v78, v184, v66
	ds_bpermute_b32 v79, v184, v67
	v_lshl_add_u64 v[80:81], v[180:181], 0, v[168:169]
	s_waitcnt vmcnt(0)
	v_lshlrev_b32_e32 v64, 16, v72
	v_and_b32_e32 v65, 0xffff0000, v72
	v_lshlrev_b32_e32 v66, 16, v73
	v_and_b32_e32 v67, 0xffff0000, v73
	v_lshlrev_b32_e32 v72, 16, v74
	v_and_b32_e32 v73, 0xffff0000, v74
	v_lshlrev_b32_e32 v74, 16, v75
	v_and_b32_e32 v75, 0xffff0000, v75
	v_pk_fma_f32 v[66:67], v[126:127], v[70:71], v[66:67]
	v_pk_fma_f32 v[64:65], v[124:125], v[68:69], v[64:65]
	s_waitcnt lgkmcnt(0)
	v_pk_fma_f32 v[70:71], v[122:123], v[78:79], v[74:75]
	v_pk_fma_f32 v[68:69], v[120:121], v[76:77], v[72:73]
	global_store_dwordx4 v[88:89], v[64:67], off offset:512 nt
	global_store_dwordx4 v[88:89], v[68:71], off offset:528 nt
	global_load_dwordx4 v[64:67], v[80:81], off nt
	ds_bpermute_b32 v68, v184, v56
	ds_bpermute_b32 v69, v184, v57
	ds_bpermute_b32 v70, v184, v58
	ds_bpermute_b32 v71, v184, v59
	v_lshl_add_u64 v[72:73], v[178:179], 0, v[152:153]
	s_waitcnt vmcnt(0)
	v_lshlrev_b32_e32 v56, 16, v64
	v_and_b32_e32 v57, 0xffff0000, v64
	v_lshlrev_b32_e32 v58, 16, v65
	v_and_b32_e32 v59, 0xffff0000, v65
	v_lshlrev_b32_e32 v64, 16, v66
	v_and_b32_e32 v65, 0xffff0000, v66
	v_lshlrev_b32_e32 v66, 16, v67
	v_and_b32_e32 v67, 0xffff0000, v67
	v_pk_fma_f32 v[58:59], v[134:135], v[62:63], v[58:59]
	v_pk_fma_f32 v[56:57], v[132:133], v[60:61], v[56:57]
	s_waitcnt lgkmcnt(0)
	v_pk_fma_f32 v[62:63], v[130:131], v[70:71], v[66:67]
	v_pk_fma_f32 v[60:61], v[128:129], v[68:69], v[64:65]
	global_store_dwordx4 v[72:73], v[56:59], off nt
	global_store_dwordx4 v[72:73], v[60:63], off offset:16 nt
	global_load_dwordx4 v[56:59], v[80:81], off offset:256 nt
	ds_bpermute_b32 v60, v184, v48
	ds_bpermute_b32 v61, v184, v49
	ds_bpermute_b32 v62, v184, v50
	ds_bpermute_b32 v63, v184, v51
	v_lshl_add_u64 v[64:65], v[180:181], 0, v[170:171]
	s_waitcnt vmcnt(0)
	v_lshlrev_b32_e32 v48, 16, v56
	v_and_b32_e32 v49, 0xffff0000, v56
	v_lshlrev_b32_e32 v50, 16, v57
	v_and_b32_e32 v51, 0xffff0000, v57
	v_lshlrev_b32_e32 v56, 16, v58
	v_and_b32_e32 v57, 0xffff0000, v58
	v_lshlrev_b32_e32 v58, 16, v59
	v_and_b32_e32 v59, 0xffff0000, v59
	v_pk_fma_f32 v[50:51], v[126:127], v[54:55], v[50:51]
	v_pk_fma_f32 v[48:49], v[124:125], v[52:53], v[48:49]
	s_waitcnt lgkmcnt(0)
	v_pk_fma_f32 v[54:55], v[122:123], v[62:63], v[58:59]
	v_pk_fma_f32 v[52:53], v[120:121], v[60:61], v[56:57]
	global_store_dwordx4 v[72:73], v[48:51], off offset:512 nt
	global_store_dwordx4 v[72:73], v[52:55], off offset:528 nt
	global_load_dwordx4 v[48:51], v[64:65], off nt
	ds_bpermute_b32 v52, v184, v40
	ds_bpermute_b32 v53, v184, v41
	ds_bpermute_b32 v54, v184, v42
	ds_bpermute_b32 v55, v184, v43
	v_lshl_add_u64 v[56:57], v[178:179], 0, v[154:155]
	s_waitcnt vmcnt(0)
	v_lshlrev_b32_e32 v40, 16, v48
	v_and_b32_e32 v41, 0xffff0000, v48
	v_lshlrev_b32_e32 v42, 16, v49
	v_and_b32_e32 v43, 0xffff0000, v49
	v_lshlrev_b32_e32 v48, 16, v50
	v_and_b32_e32 v49, 0xffff0000, v50
	v_lshlrev_b32_e32 v50, 16, v51
	v_and_b32_e32 v51, 0xffff0000, v51
	v_pk_fma_f32 v[42:43], v[134:135], v[46:47], v[42:43]
	v_pk_fma_f32 v[40:41], v[132:133], v[44:45], v[40:41]
	s_waitcnt lgkmcnt(0)
	v_pk_fma_f32 v[46:47], v[130:131], v[54:55], v[50:51]
	v_pk_fma_f32 v[44:45], v[128:129], v[52:53], v[48:49]
	global_store_dwordx4 v[56:57], v[40:43], off nt
	global_store_dwordx4 v[56:57], v[44:47], off offset:16 nt
	global_load_dwordx4 v[40:43], v[64:65], off offset:256 nt
	ds_bpermute_b32 v44, v184, v32
	ds_bpermute_b32 v45, v184, v33
	ds_bpermute_b32 v46, v184, v34
	ds_bpermute_b32 v47, v184, v35
	v_lshl_add_u64 v[48:49], v[180:181], 0, v[172:173]
	s_waitcnt vmcnt(0)
	v_lshlrev_b32_e32 v32, 16, v40
	v_and_b32_e32 v33, 0xffff0000, v40
	v_lshlrev_b32_e32 v34, 16, v41
	v_and_b32_e32 v35, 0xffff0000, v41
	v_lshlrev_b32_e32 v40, 16, v42
	v_and_b32_e32 v41, 0xffff0000, v42
	v_lshlrev_b32_e32 v42, 16, v43
	v_and_b32_e32 v43, 0xffff0000, v43
	v_pk_fma_f32 v[34:35], v[126:127], v[38:39], v[34:35]
	v_pk_fma_f32 v[32:33], v[124:125], v[36:37], v[32:33]
	s_waitcnt lgkmcnt(0)
	v_pk_fma_f32 v[38:39], v[122:123], v[46:47], v[42:43]
	v_pk_fma_f32 v[36:37], v[120:121], v[44:45], v[40:41]
	global_store_dwordx4 v[56:57], v[32:35], off offset:512 nt
	global_store_dwordx4 v[56:57], v[36:39], off offset:528 nt
	global_load_dwordx4 v[32:35], v[48:49], off nt
	ds_bpermute_b32 v36, v184, v24
	ds_bpermute_b32 v37, v184, v25
	ds_bpermute_b32 v38, v184, v26
	ds_bpermute_b32 v39, v184, v27
	v_lshl_add_u64 v[40:41], v[178:179], 0, v[156:157]
	s_waitcnt vmcnt(0)
	v_lshlrev_b32_e32 v24, 16, v32
	v_and_b32_e32 v25, 0xffff0000, v32
	v_lshlrev_b32_e32 v26, 16, v33
	v_and_b32_e32 v27, 0xffff0000, v33
	v_lshlrev_b32_e32 v32, 16, v34
	v_and_b32_e32 v33, 0xffff0000, v34
	v_lshlrev_b32_e32 v34, 16, v35
	v_and_b32_e32 v35, 0xffff0000, v35
	v_pk_fma_f32 v[26:27], v[134:135], v[30:31], v[26:27]
	v_pk_fma_f32 v[24:25], v[132:133], v[28:29], v[24:25]
	s_waitcnt lgkmcnt(0)
	v_pk_fma_f32 v[30:31], v[130:131], v[38:39], v[34:35]
	v_pk_fma_f32 v[28:29], v[128:129], v[36:37], v[32:33]
	global_store_dwordx4 v[40:41], v[24:27], off nt
	global_store_dwordx4 v[40:41], v[28:31], off offset:16 nt
	global_load_dwordx4 v[24:27], v[48:49], off offset:256 nt
	ds_bpermute_b32 v28, v184, v16
	ds_bpermute_b32 v29, v184, v17
	ds_bpermute_b32 v30, v184, v18
	ds_bpermute_b32 v31, v184, v19
	v_lshl_add_u64 v[32:33], v[180:181], 0, v[174:175]
	s_waitcnt vmcnt(0)
	v_lshlrev_b32_e32 v16, 16, v24
	v_and_b32_e32 v17, 0xffff0000, v24
	v_lshlrev_b32_e32 v18, 16, v25
	v_and_b32_e32 v19, 0xffff0000, v25
	v_lshlrev_b32_e32 v24, 16, v26
	v_and_b32_e32 v25, 0xffff0000, v26
	v_lshlrev_b32_e32 v26, 16, v27
	v_and_b32_e32 v27, 0xffff0000, v27
	v_pk_fma_f32 v[18:19], v[126:127], v[22:23], v[18:19]
	v_pk_fma_f32 v[16:17], v[124:125], v[20:21], v[16:17]
	s_waitcnt lgkmcnt(0)
	v_pk_fma_f32 v[22:23], v[122:123], v[30:31], v[26:27]
	v_pk_fma_f32 v[20:21], v[120:121], v[28:29], v[24:25]
	global_store_dwordx4 v[40:41], v[16:19], off offset:512 nt
	global_store_dwordx4 v[40:41], v[20:23], off offset:528 nt
	global_load_dwordx4 v[16:19], v[32:33], off nt
	ds_bpermute_b32 v20, v184, v8
	ds_bpermute_b32 v21, v184, v9
	ds_bpermute_b32 v22, v184, v10
	ds_bpermute_b32 v23, v184, v11
	v_lshl_add_u64 v[24:25], v[178:179], 0, v[158:159]
	s_waitcnt vmcnt(0)
	v_lshlrev_b32_e32 v8, 16, v16
	v_and_b32_e32 v9, 0xffff0000, v16
	v_lshlrev_b32_e32 v10, 16, v17
	v_and_b32_e32 v11, 0xffff0000, v17
	v_lshlrev_b32_e32 v16, 16, v18
	v_and_b32_e32 v17, 0xffff0000, v18
	v_lshlrev_b32_e32 v18, 16, v19
	v_and_b32_e32 v19, 0xffff0000, v19
	v_pk_fma_f32 v[10:11], v[134:135], v[14:15], v[10:11]
	v_pk_fma_f32 v[8:9], v[132:133], v[12:13], v[8:9]
	s_waitcnt lgkmcnt(0)
	v_pk_fma_f32 v[14:15], v[130:131], v[22:23], v[18:19]
	v_pk_fma_f32 v[12:13], v[128:129], v[20:21], v[16:17]
	global_store_dwordx4 v[24:25], v[8:11], off nt
	global_store_dwordx4 v[24:25], v[12:15], off offset:16 nt
	global_load_dwordx4 v[8:11], v[32:33], off offset:256 nt
	ds_bpermute_b32 v12, v184, v0
	ds_bpermute_b32 v13, v184, v1
	ds_bpermute_b32 v14, v184, v2
	ds_bpermute_b32 v15, v184, v3
	s_waitcnt vmcnt(0)
	v_lshlrev_b32_e32 v0, 16, v8
	v_and_b32_e32 v1, 0xffff0000, v8
	v_lshlrev_b32_e32 v2, 16, v9
	v_and_b32_e32 v3, 0xffff0000, v9
	v_lshlrev_b32_e32 v8, 16, v10
	v_and_b32_e32 v9, 0xffff0000, v10
	v_lshlrev_b32_e32 v10, 16, v11
	v_and_b32_e32 v11, 0xffff0000, v11
	v_pk_fma_f32 v[2:3], v[126:127], v[6:7], v[2:3]
	v_pk_fma_f32 v[0:1], v[124:125], v[4:5], v[0:1]
	s_waitcnt lgkmcnt(0)
	v_pk_fma_f32 v[6:7], v[122:123], v[14:15], v[10:11]
	v_pk_fma_f32 v[4:5], v[120:121], v[12:13], v[8:9]
	global_store_dwordx4 v[24:25], v[0:3], off offset:512 nt
	global_store_dwordx4 v[24:25], v[4:7], off offset:528 nt
	s_cbranch_vccnz .LBB0_896
	s_andn2_b64 vcc, exec, s[10:11]
	s_cbranch_vccnz .LBB0_895
	s_barrier
	s_branch .LBB0_895
